# embed/rowstat (both layers): the four per-row chunk loads hoisted and the 4-iteration loop unrolled with counted vmcnt waits
# baseline (speedup 1.0000x reference)
.LBB0_771:
	v_lshl_add_u64 v[66:67], v[10:11], 0, s[6:7]
	v_lshl_add_u64 v[68:69], v[66:67], 0, s[6:7]
	v_lshl_add_u64 v[70:71], v[68:69], 0, s[6:7]
	global_load_dwordx2 v[72:73], v[10:11], off
	global_load_dwordx2 v[74:75], v[66:67], off
	global_load_dwordx2 v[76:77], v[68:69], off
	global_load_dwordx2 v[78:79], v[70:71], off
	s_waitcnt lgkmcnt(0)
	v_add_u32_e32 v56, s4, v21
	ds_read_b128 v[14:17], v56
	ds_read_b128 v[32:35], v56 offset:16
	ds_read_b128 v[36:39], v56 offset:32
	ds_read_b128 v[40:43], v56 offset:48
	ds_read_b128 v[44:47], v56 offset:64
	ds_read_b128 v[48:51], v56 offset:80
	ds_read_b128 v[52:55], v56 offset:96
	ds_read_b128 v[56:59], v56 offset:112
	s_addk_i32 s4, 0x2000
	v_lshl_add_u64 v[10:11], v[10:11], 0, s[6:7]
	s_cmpk_eq_u32 s4, 0x8000
	s_waitcnt vmcnt(3)
	v_lshlrev_b32_e32 v60, 16, v72
	v_lshlrev_b32_e32 v63, 16, v73
	v_and_b32_e32 v62, 0xffff0000, v72
	v_fmac_f32_e32 v3, v60, v60
	v_pk_mul_f32 v[64:65], v[62:63], v[62:63]
	s_waitcnt lgkmcnt(7)
	v_pk_fma_f32 v[12:13], v[14:15], v[60:61], v[12:13] op_sel_hi:[1,0,1]
	v_pk_fma_f32 v[8:9], v[16:17], v[60:61], v[8:9] op_sel_hi:[1,0,1]
	s_waitcnt lgkmcnt(6)
	v_pk_fma_f32 v[6:7], v[32:33], v[60:61], v[6:7] op_sel_hi:[1,0,1]
	v_pk_fma_f32 v[4:5], v[34:35], v[60:61], v[4:5] op_sel_hi:[1,0,1]
	v_add_f32_e32 v3, v64, v3
	s_waitcnt lgkmcnt(5)
	v_pk_fma_f32 v[12:13], v[36:37], v[62:63], v[12:13] op_sel_hi:[1,0,1]
	v_pk_fma_f32 v[8:9], v[38:39], v[62:63], v[8:9] op_sel_hi:[1,0,1]
	s_waitcnt lgkmcnt(4)
	v_pk_fma_f32 v[6:7], v[40:41], v[62:63], v[6:7] op_sel_hi:[1,0,1]
	v_pk_fma_f32 v[4:5], v[42:43], v[62:63], v[4:5] op_sel_hi:[1,0,1]
	v_and_b32_e32 v18, 0xffff0000, v73
	v_add_f32_e32 v3, v65, v3
	s_waitcnt lgkmcnt(3)
	v_pk_fma_f32 v[12:13], v[44:45], v[62:63], v[12:13] op_sel:[0,1,0]
	v_pk_fma_f32 v[8:9], v[46:47], v[62:63], v[8:9] op_sel:[0,1,0]
	s_waitcnt lgkmcnt(2)
	v_pk_fma_f32 v[6:7], v[48:49], v[62:63], v[6:7] op_sel:[0,1,0]
	v_pk_fma_f32 v[4:5], v[50:51], v[62:63], v[4:5] op_sel:[0,1,0]
	v_fmac_f32_e32 v3, v18, v18
	s_waitcnt lgkmcnt(1)
	v_pk_fma_f32 v[12:13], v[52:53], v[18:19], v[12:13] op_sel_hi:[1,0,1]
	v_pk_fma_f32 v[8:9], v[54:55], v[18:19], v[8:9] op_sel_hi:[1,0,1]
	s_waitcnt lgkmcnt(0)
	v_pk_fma_f32 v[6:7], v[56:57], v[18:19], v[6:7] op_sel_hi:[1,0,1]
	v_pk_fma_f32 v[4:5], v[58:59], v[18:19], v[4:5] op_sel_hi:[1,0,1]
	s_waitcnt lgkmcnt(0)
	v_add_u32_e32 v56, s4, v21
	ds_read_b128 v[14:17], v56
	ds_read_b128 v[32:35], v56 offset:16
	ds_read_b128 v[36:39], v56 offset:32
	ds_read_b128 v[40:43], v56 offset:48
	ds_read_b128 v[44:47], v56 offset:64
	ds_read_b128 v[48:51], v56 offset:80
	ds_read_b128 v[52:55], v56 offset:96
	ds_read_b128 v[56:59], v56 offset:112
	s_addk_i32 s4, 0x2000
	v_lshl_add_u64 v[10:11], v[10:11], 0, s[6:7]
	s_cmpk_eq_u32 s4, 0x8000
	s_waitcnt vmcnt(2)
	v_lshlrev_b32_e32 v60, 16, v74
	v_lshlrev_b32_e32 v63, 16, v75
	v_and_b32_e32 v62, 0xffff0000, v74
	v_fmac_f32_e32 v3, v60, v60
	v_pk_mul_f32 v[64:65], v[62:63], v[62:63]
	s_waitcnt lgkmcnt(7)
	v_pk_fma_f32 v[12:13], v[14:15], v[60:61], v[12:13] op_sel_hi:[1,0,1]
	v_pk_fma_f32 v[8:9], v[16:17], v[60:61], v[8:9] op_sel_hi:[1,0,1]
	s_waitcnt lgkmcnt(6)
	v_pk_fma_f32 v[6:7], v[32:33], v[60:61], v[6:7] op_sel_hi:[1,0,1]
	v_pk_fma_f32 v[4:5], v[34:35], v[60:61], v[4:5] op_sel_hi:[1,0,1]
	v_add_f32_e32 v3, v64, v3
	s_waitcnt lgkmcnt(5)
	v_pk_fma_f32 v[12:13], v[36:37], v[62:63], v[12:13] op_sel_hi:[1,0,1]
	v_pk_fma_f32 v[8:9], v[38:39], v[62:63], v[8:9] op_sel_hi:[1,0,1]
	s_waitcnt lgkmcnt(4)
	v_pk_fma_f32 v[6:7], v[40:41], v[62:63], v[6:7] op_sel_hi:[1,0,1]
	v_pk_fma_f32 v[4:5], v[42:43], v[62:63], v[4:5] op_sel_hi:[1,0,1]
	v_and_b32_e32 v18, 0xffff0000, v75
	v_add_f32_e32 v3, v65, v3
	s_waitcnt lgkmcnt(3)
	v_pk_fma_f32 v[12:13], v[44:45], v[62:63], v[12:13] op_sel:[0,1,0]
	v_pk_fma_f32 v[8:9], v[46:47], v[62:63], v[8:9] op_sel:[0,1,0]
	s_waitcnt lgkmcnt(2)
	v_pk_fma_f32 v[6:7], v[48:49], v[62:63], v[6:7] op_sel:[0,1,0]
	v_pk_fma_f32 v[4:5], v[50:51], v[62:63], v[4:5] op_sel:[0,1,0]
	v_fmac_f32_e32 v3, v18, v18
	s_waitcnt lgkmcnt(1)
	v_pk_fma_f32 v[12:13], v[52:53], v[18:19], v[12:13] op_sel_hi:[1,0,1]
	v_pk_fma_f32 v[8:9], v[54:55], v[18:19], v[8:9] op_sel_hi:[1,0,1]
	s_waitcnt lgkmcnt(0)
	v_pk_fma_f32 v[6:7], v[56:57], v[18:19], v[6:7] op_sel_hi:[1,0,1]
	v_pk_fma_f32 v[4:5], v[58:59], v[18:19], v[4:5] op_sel_hi:[1,0,1]
	s_waitcnt lgkmcnt(0)
	v_add_u32_e32 v56, s4, v21
	ds_read_b128 v[14:17], v56
	ds_read_b128 v[32:35], v56 offset:16
	ds_read_b128 v[36:39], v56 offset:32
	ds_read_b128 v[40:43], v56 offset:48
	ds_read_b128 v[44:47], v56 offset:64
	ds_read_b128 v[48:51], v56 offset:80
	ds_read_b128 v[52:55], v56 offset:96
	ds_read_b128 v[56:59], v56 offset:112
	s_addk_i32 s4, 0x2000
	v_lshl_add_u64 v[10:11], v[10:11], 0, s[6:7]
	s_cmpk_eq_u32 s4, 0x8000
	s_waitcnt vmcnt(1)
	v_lshlrev_b32_e32 v60, 16, v76
	v_lshlrev_b32_e32 v63, 16, v77
	v_and_b32_e32 v62, 0xffff0000, v76
	v_fmac_f32_e32 v3, v60, v60
	v_pk_mul_f32 v[64:65], v[62:63], v[62:63]
	s_waitcnt lgkmcnt(7)
	v_pk_fma_f32 v[12:13], v[14:15], v[60:61], v[12:13] op_sel_hi:[1,0,1]
	v_pk_fma_f32 v[8:9], v[16:17], v[60:61], v[8:9] op_sel_hi:[1,0,1]
	s_waitcnt lgkmcnt(6)
	v_pk_fma_f32 v[6:7], v[32:33], v[60:61], v[6:7] op_sel_hi:[1,0,1]
	v_pk_fma_f32 v[4:5], v[34:35], v[60:61], v[4:5] op_sel_hi:[1,0,1]
	v_add_f32_e32 v3, v64, v3
	s_waitcnt lgkmcnt(5)
	v_pk_fma_f32 v[12:13], v[36:37], v[62:63], v[12:13] op_sel_hi:[1,0,1]
	v_pk_fma_f32 v[8:9], v[38:39], v[62:63], v[8:9] op_sel_hi:[1,0,1]
	s_waitcnt lgkmcnt(4)
	v_pk_fma_f32 v[6:7], v[40:41], v[62:63], v[6:7] op_sel_hi:[1,0,1]
	v_pk_fma_f32 v[4:5], v[42:43], v[62:63], v[4:5] op_sel_hi:[1,0,1]
	v_and_b32_e32 v18, 0xffff0000, v77
	v_add_f32_e32 v3, v65, v3
	s_waitcnt lgkmcnt(3)
	v_pk_fma_f32 v[12:13], v[44:45], v[62:63], v[12:13] op_sel:[0,1,0]
	v_pk_fma_f32 v[8:9], v[46:47], v[62:63], v[8:9] op_sel:[0,1,0]
	s_waitcnt lgkmcnt(2)
	v_pk_fma_f32 v[6:7], v[48:49], v[62:63], v[6:7] op_sel:[0,1,0]
	v_pk_fma_f32 v[4:5], v[50:51], v[62:63], v[4:5] op_sel:[0,1,0]
	v_fmac_f32_e32 v3, v18, v18
	s_waitcnt lgkmcnt(1)
	v_pk_fma_f32 v[12:13], v[52:53], v[18:19], v[12:13] op_sel_hi:[1,0,1]
	v_pk_fma_f32 v[8:9], v[54:55], v[18:19], v[8:9] op_sel_hi:[1,0,1]
	s_waitcnt lgkmcnt(0)
	v_pk_fma_f32 v[6:7], v[56:57], v[18:19], v[6:7] op_sel_hi:[1,0,1]
	v_pk_fma_f32 v[4:5], v[58:59], v[18:19], v[4:5] op_sel_hi:[1,0,1]
	s_waitcnt lgkmcnt(0)
	v_add_u32_e32 v56, s4, v21
	ds_read_b128 v[14:17], v56
	ds_read_b128 v[32:35], v56 offset:16
	ds_read_b128 v[36:39], v56 offset:32
	ds_read_b128 v[40:43], v56 offset:48
	ds_read_b128 v[44:47], v56 offset:64
	ds_read_b128 v[48:51], v56 offset:80
	ds_read_b128 v[52:55], v56 offset:96
	ds_read_b128 v[56:59], v56 offset:112
	s_addk_i32 s4, 0x2000
	v_lshl_add_u64 v[10:11], v[10:11], 0, s[6:7]
	s_cmpk_eq_u32 s4, 0x8000
	s_waitcnt vmcnt(0)
	v_lshlrev_b32_e32 v60, 16, v78
	v_lshlrev_b32_e32 v63, 16, v79
	v_and_b32_e32 v62, 0xffff0000, v78
	v_fmac_f32_e32 v3, v60, v60
	v_pk_mul_f32 v[64:65], v[62:63], v[62:63]
	s_waitcnt lgkmcnt(7)
	v_pk_fma_f32 v[12:13], v[14:15], v[60:61], v[12:13] op_sel_hi:[1,0,1]
	v_pk_fma_f32 v[8:9], v[16:17], v[60:61], v[8:9] op_sel_hi:[1,0,1]
	s_waitcnt lgkmcnt(6)
	v_pk_fma_f32 v[6:7], v[32:33], v[60:61], v[6:7] op_sel_hi:[1,0,1]
	v_pk_fma_f32 v[4:5], v[34:35], v[60:61], v[4:5] op_sel_hi:[1,0,1]
	v_add_f32_e32 v3, v64, v3
	s_waitcnt lgkmcnt(5)
	v_pk_fma_f32 v[12:13], v[36:37], v[62:63], v[12:13] op_sel_hi:[1,0,1]
	v_pk_fma_f32 v[8:9], v[38:39], v[62:63], v[8:9] op_sel_hi:[1,0,1]
	s_waitcnt lgkmcnt(4)
	v_pk_fma_f32 v[6:7], v[40:41], v[62:63], v[6:7] op_sel_hi:[1,0,1]
	v_pk_fma_f32 v[4:5], v[42:43], v[62:63], v[4:5] op_sel_hi:[1,0,1]
	v_and_b32_e32 v18, 0xffff0000, v79
	v_add_f32_e32 v3, v65, v3
	s_waitcnt lgkmcnt(3)
	v_pk_fma_f32 v[12:13], v[44:45], v[62:63], v[12:13] op_sel:[0,1,0]
	v_pk_fma_f32 v[8:9], v[46:47], v[62:63], v[8:9] op_sel:[0,1,0]
	s_waitcnt lgkmcnt(2)
	v_pk_fma_f32 v[6:7], v[48:49], v[62:63], v[6:7] op_sel:[0,1,0]
	v_pk_fma_f32 v[4:5], v[50:51], v[62:63], v[4:5] op_sel:[0,1,0]
	v_fmac_f32_e32 v3, v18, v18
	s_waitcnt lgkmcnt(1)
	v_pk_fma_f32 v[12:13], v[52:53], v[18:19], v[12:13] op_sel_hi:[1,0,1]
	v_pk_fma_f32 v[8:9], v[54:55], v[18:19], v[8:9] op_sel_hi:[1,0,1]
	s_waitcnt lgkmcnt(0)
	v_pk_fma_f32 v[6:7], v[56:57], v[18:19], v[6:7] op_sel_hi:[1,0,1]
	v_pk_fma_f32 v[4:5], v[58:59], v[18:19], v[4:5] op_sel_hi:[1,0,1]
	v_add_f32_dpp v3, v3, v3 quad_perm:[1,0,3,2] row_mask:0xf bank_mask:0xf bound_ctrl:1
	v_mov_b32_dpp v10, v12 quad_perm:[1,0,3,2] row_mask:0xf bank_mask:0xf bound_ctrl:1
	v_mov_b32_dpp v11, v13 quad_perm:[1,0,3,2] row_mask:0xf bank_mask:0xf bound_ctrl:1
	v_add_f32_dpp v3, v3, v3 quad_perm:[2,3,0,1] row_mask:0xf bank_mask:0xf bound_ctrl:1
	v_mov_b32_dpp v15, v9 quad_perm:[1,0,3,2] row_mask:0xf bank_mask:0xf bound_ctrl:1
	v_pk_add_f32 v[10:11], v[12:13], v[10:11]
	v_add_f32_dpp v3, v3, v3 row_half_mirror row_mask:0xf bank_mask:0xf bound_ctrl:1
	v_mov_b32_dpp v18, v4 quad_perm:[1,0,3,2] row_mask:0xf bank_mask:0xf bound_ctrl:1
	v_mov_b32_dpp v12, v10 quad_perm:[2,3,0,1] row_mask:0xf bank_mask:0xf bound_ctrl:1
	v_add_f32_dpp v3, v3, v3 row_mirror row_mask:0xf bank_mask:0xf bound_ctrl:1
	ds_bpermute_b32 v14, v28, v3
	v_mov_b32_dpp v13, v11 quad_perm:[2,3,0,1] row_mask:0xf bank_mask:0xf bound_ctrl:1
	v_pk_add_f32 v[10:11], v[10:11], v[12:13]
	v_mov_b32_dpp v19, v5 quad_perm:[1,0,3,2] row_mask:0xf bank_mask:0xf bound_ctrl:1
	v_pk_add_f32 v[4:5], v[4:5], v[18:19]
	s_waitcnt lgkmcnt(0)
	v_add_f32_e32 v3, v3, v14
	v_mov_b32_dpp v14, v8 quad_perm:[1,0,3,2] row_mask:0xf bank_mask:0xf bound_ctrl:1
	v_pk_add_f32 v[8:9], v[8:9], v[14:15]
	v_mov_b32_dpp v12, v10 row_half_mirror row_mask:0xf bank_mask:0xf bound_ctrl:1
	v_mov_b32_dpp v13, v11 row_half_mirror row_mask:0xf bank_mask:0xf bound_ctrl:1
	v_mov_b32_dpp v14, v8 quad_perm:[2,3,0,1] row_mask:0xf bank_mask:0xf bound_ctrl:1
	v_mov_b32_dpp v15, v9 quad_perm:[2,3,0,1] row_mask:0xf bank_mask:0xf bound_ctrl:1
	v_pk_add_f32 v[8:9], v[8:9], v[14:15]
	v_pk_add_f32 v[10:11], v[10:11], v[12:13]
	v_mov_b32_dpp v18, v4 quad_perm:[2,3,0,1] row_mask:0xf bank_mask:0xf bound_ctrl:1
	v_mov_b32_dpp v14, v8 row_half_mirror row_mask:0xf bank_mask:0xf bound_ctrl:1
	v_mov_b32_dpp v15, v9 row_half_mirror row_mask:0xf bank_mask:0xf bound_ctrl:1
	v_pk_add_f32 v[8:9], v[8:9], v[14:15]
	v_mov_b32_dpp v12, v10 row_mirror row_mask:0xf bank_mask:0xf bound_ctrl:1
	v_mov_b32_dpp v13, v11 row_mirror row_mask:0xf bank_mask:0xf bound_ctrl:1
	v_mov_b32_dpp v14, v8 row_mirror row_mask:0xf bank_mask:0xf bound_ctrl:1
	v_mov_b32_dpp v15, v9 row_mirror row_mask:0xf bank_mask:0xf bound_ctrl:1
	v_pk_add_f32 v[10:11], v[10:11], v[12:13]
	v_pk_add_f32 v[14:15], v[8:9], v[14:15]
	ds_bpermute_b32 v12, v28, v10
	ds_bpermute_b32 v13, v28, v11
	ds_bpermute_b32 v16, v28, v14
	ds_bpermute_b32 v17, v28, v15
	v_mov_b32_dpp v19, v5 quad_perm:[2,3,0,1] row_mask:0xf bank_mask:0xf bound_ctrl:1
	v_pk_add_f32 v[4:5], v[4:5], v[18:19]
	s_waitcnt lgkmcnt(2)
	v_pk_add_f32 v[8:9], v[10:11], v[12:13]
	ds_bpermute_b32 v32, v29, v3
	s_waitcnt lgkmcnt(1)
	v_pk_add_f32 v[12:13], v[14:15], v[16:17]
	v_mov_b32_dpp v16, v6 quad_perm:[1,0,3,2] row_mask:0xf bank_mask:0xf bound_ctrl:1
	v_mov_b32_dpp v17, v7 quad_perm:[1,0,3,2] row_mask:0xf bank_mask:0xf bound_ctrl:1
	v_pk_add_f32 v[6:7], v[6:7], v[16:17]
	v_mov_b32_dpp v18, v4 row_half_mirror row_mask:0xf bank_mask:0xf bound_ctrl:1
	v_mov_b32_dpp v19, v5 row_half_mirror row_mask:0xf bank_mask:0xf bound_ctrl:1
	v_mov_b32_dpp v16, v6 quad_perm:[2,3,0,1] row_mask:0xf bank_mask:0xf bound_ctrl:1
	v_mov_b32_dpp v17, v7 quad_perm:[2,3,0,1] row_mask:0xf bank_mask:0xf bound_ctrl:1
	v_pk_add_f32 v[6:7], v[6:7], v[16:17]
	v_pk_add_f32 v[4:5], v[4:5], v[18:19]
	ds_bpermute_b32 v10, v29, v8
	v_mov_b32_dpp v16, v6 row_half_mirror row_mask:0xf bank_mask:0xf bound_ctrl:1
	v_mov_b32_dpp v17, v7 row_half_mirror row_mask:0xf bank_mask:0xf bound_ctrl:1
	v_pk_add_f32 v[6:7], v[6:7], v[16:17]
	v_mov_b32_dpp v18, v4 row_mirror row_mask:0xf bank_mask:0xf bound_ctrl:1
	v_mov_b32_dpp v19, v5 row_mirror row_mask:0xf bank_mask:0xf bound_ctrl:1
	v_mov_b32_dpp v16, v6 row_mirror row_mask:0xf bank_mask:0xf bound_ctrl:1
	v_mov_b32_dpp v17, v7 row_mirror row_mask:0xf bank_mask:0xf bound_ctrl:1
	v_pk_add_f32 v[6:7], v[6:7], v[16:17]
	v_pk_add_f32 v[18:19], v[4:5], v[18:19]
	ds_bpermute_b32 v16, v28, v6
	ds_bpermute_b32 v17, v28, v7
	ds_bpermute_b32 v34, v28, v18
	ds_bpermute_b32 v35, v28, v19
	ds_bpermute_b32 v11, v29, v9
	ds_bpermute_b32 v14, v29, v12
	s_waitcnt lgkmcnt(4)
	v_pk_add_f32 v[4:5], v[6:7], v[16:17]
	ds_bpermute_b32 v15, v29, v13
	s_waitcnt lgkmcnt(3)
	v_pk_add_f32 v[16:17], v[18:19], v[34:35]
	ds_bpermute_b32 v6, v29, v4
	ds_bpermute_b32 v7, v29, v5
	ds_bpermute_b32 v18, v29, v16
	ds_bpermute_b32 v19, v29, v17
	s_and_saveexec_b64 s[12:13], s[0:1]
	s_cbranch_execz .LBB0_769
	v_add_f32_e32 v3, v3, v32
	v_fmamk_f32 v3, v3, 0x3a800000, v23
	v_mul_f32_e32 v32, 0x4b800000, v3
	v_cmp_gt_f32_e64 s[4:5], s18, v3
	s_waitcnt lgkmcnt(6)
	v_pk_add_f32 v[8:9], v[8:9], v[10:11]
	s_waitcnt lgkmcnt(4)
	v_pk_add_f32 v[10:11], v[12:13], v[14:15]
	v_cndmask_b32_e64 v3, v3, v32, s[4:5]
	v_rsq_f32_e32 v34, v3
	v_ashrrev_i32_e32 v3, 31, v2
	v_lshlrev_b64 v[32:33], 5, v[2:3]
	s_waitcnt lgkmcnt(2)
	v_pk_add_f32 v[4:5], v[4:5], v[6:7]
	v_mul_f32_e32 v35, 0x45800000, v34
	v_cndmask_b32_e64 v34, v34, v35, s[4:5]
	s_waitcnt lgkmcnt(0)
	v_pk_add_f32 v[6:7], v[16:17], v[18:19]
	v_lshl_add_u64 v[32:33], s[2:3], 0, v[32:33]
	v_pk_mul_f32 v[8:9], v[8:9], v[34:35] op_sel_hi:[1,0]
	v_pk_mul_f32 v[10:11], v[34:35], v[10:11] op_sel_hi:[0,1]
	v_pk_mul_f32 v[4:5], v[34:35], v[4:5] op_sel_hi:[0,1]
	v_pk_mul_f32 v[6:7], v[34:35], v[6:7] op_sel_hi:[0,1]
	v_lshl_add_u64 v[2:3], v[2:3], 2, s[90:91]
	global_store_dwordx4 v[32:33], v[8:11], off
	global_store_dwordx4 v[32:33], v[4:7], off offset:16
	global_store_dword v[2:3], v34, off
	s_branch .LBB0_769
